# attention key loop: QK blocks keep 5 K-fragment LDS reads in flight with counted lgkmcnt (2 spare quads), same accumulation order
# speedup vs baseline: 1.0075x; 1.0040x over previous
; #define MFMA(a, b, c) __builtin_amdgcn_mfma_f32_32x32x16_bf16((a), (b), (c), 0, 0, 0)
; DI unsigned pk_bf16(float lo, float hi) { f32x2v v = {lo, hi}; bf16x2v b = __builtin_convertvector(v, bf16x2v); return __builtin_bit_cast(unsigned, b); }
; #define SB_ __builtin_amdgcn_sched_barrier(0)
; DI void attn_item64(const Params& p, int it, char* smem) {
;     ...
;     SB_;
; #pragma unroll
;     for (int t2 = 0; t2 < 2; ++t2) {
;       const char* kpe = cur + (t2 * 32 + r) * KROW + swo;
;       const char* kpo = kpe - 2 * sb32;
;       f32x16 sa, sb;
;       { const bf16x8 kf = *(const bf16x8*)(kpe); sa = MFMA(kf, qfa[0], sinit); sb = MFMA(kf, qfb[0], sinit); }
; #pragma unroll
;       for (int c = 1; c < 6; ++c) { const bf16x8 kf = *(const bf16x8*)(((c & 1) ? kpo : kpe) + c * 32); sa = MFMA(kf, qfa[c], sa); sb = MFMA(kf, qfb[c], sb); }
;       SB_;
;       float lsa = 0.f, lsb = 0.f;
; #pragma unroll
;       for (int i = 0; i < 16; ++i) { const float e = __builtin_amdgcn_exp2f(sa[i]); sa[i] = e; lsa += e; const float f = __builtin_amdgcn_exp2f(sb[i]); sb[i] = f; lsb += f; }
;       la += lsa; lb += lsb;
;       SB_;
; #pragma unroll
;       for (int s2 = 0; s2 < 2; ++s2) {
;         uint4 pu, pv;
;         pu.x = pk_bf16(sa[8 * s2 + 0], sa[8 * s2 + 1]); pu.y = pk_bf16(sa[8 * s2 + 2], sa[8 * s2 + 3]); pu.z = pk_bf16(sa[8 * s2 + 4], sa[8 * s2 + 5]); pu.w = pk_bf16(sa[8 * s2 + 6], sa[8 * s2 + 7]);
;         pv.x = pk_bf16(sb[8 * s2 + 0], sb[8 * s2 + 1]); pv.y = pk_bf16(sb[8 * s2 + 2], sb[8 * s2 + 3]); pv.z = pk_bf16(sb[8 * s2 + 4], sb[8 * s2 + 5]); pv.w = pk_bf16(sb[8 * s2 + 6], sb[8 * s2 + 7]);
;         const bf16x8 pa_ = __builtin_bit_cast(bf16x8, pu), pb_ = __builtin_bit_cast(bf16x8, pv);
; #pragma unroll
;         for (int vt = 0; vt < 2; ++vt) {
;           const char* vp = cur + KBYTES + (vt * 32 + r) * VROW + (t2 * 32 + 16 * s2 + 4 * hh) * 2;
;           const uint2 lo = *(const uint2*)(vp), hi = *(const uint2*)(vp + 16);
;           uint4 vu; vu.x = lo.x; vu.y = lo.y; vu.z = hi.x; vu.w = hi.y;
;           const bf16x8 vf = __builtin_bit_cast(bf16x8, vu);
;           oa[vt] = MFMA(vf, pa_, oa[vt]);
;           ob[vt] = MFMA(vf, pb_, ob[vt]);
;         }
;       }
.LBB0_548:
	s_or_b64 exec, exec, s[4:5]
	global_load_dwordx4 v[160:163], v[170:171], off
	s_cmp_eq_u32 s7, 1
	s_cselect_b32 s4, 0, 0x5200
	v_or_b32_e32 v80, s4, v211
	v_add_u32_e32 v80, v80, v210
	v_or_b32_e32 v81, s4, v164
	v_add_u32_e32 v168, v80, v212
	v_add3_u32 v213, v80, v207, v206
	v_add_u32_e32 v80, s6, v209
	v_add_u32_e32 v188, v168, v206
	v_add_u32_e32 v195, v81, v208
	v_add_u32_e32 v238, 0x3000, v80
	ds_read_b128 v[176:179], v168
	ds_read_b128 v[242:245], v188 offset:32
	ds_read_b128 v[180:183], v168 offset:64
	ds_read_b128 v[246:249], v188 offset:96
	ds_read_b128 v[184:187], v168 offset:128
	s_waitcnt lgkmcnt(4)
	v_mfma_f32_32x32x16_bf16 v[80:95], v[176:179], v[152:155], v[64:79]
	v_mfma_f32_32x32x16_bf16 v[96:111], v[176:179], v[156:159], v[64:79]
	ds_read_b128 v[176:179], v188 offset:160
	s_waitcnt lgkmcnt(4)
	v_mfma_f32_32x32x16_bf16 v[80:95], v[242:245], v[136:139], v[80:95]
	v_mfma_f32_32x32x16_bf16 v[96:111], v[242:245], v[140:143], v[96:111]
	s_waitcnt lgkmcnt(3)
	v_mfma_f32_32x32x16_bf16 v[80:95], v[180:183], v[144:147], v[80:95]
	v_mfma_f32_32x32x16_bf16 v[96:111], v[180:183], v[148:151], v[96:111]
	s_waitcnt lgkmcnt(2)
	v_mfma_f32_32x32x16_bf16 v[80:95], v[246:249], v[112:115], v[80:95]
	v_mfma_f32_32x32x16_bf16 v[96:111], v[246:249], v[124:127], v[96:111]
	s_waitcnt lgkmcnt(1)
	v_mfma_f32_32x32x16_bf16 v[80:95], v[184:187], v[128:131], v[80:95]
	v_mfma_f32_32x32x16_bf16 v[96:111], v[184:187], v[132:135], v[96:111]
	s_waitcnt lgkmcnt(0)
	v_mfma_f32_32x32x16_bf16 v[80:95], v[176:179], v[116:119], v[80:95]
	v_mfma_f32_32x32x16_bf16 v[96:111], v[176:179], v[120:123], v[96:111]
	s_nop 10
	v_exp_f32_e32 v214, v80
	v_exp_f32_e32 v215, v81
	v_exp_f32_e32 v216, v82
	v_exp_f32_e32 v217, v83
	v_add_f32_e32 v80, 0, v214
	v_exp_f32_e32 v218, v84
	v_add_f32_e32 v80, v215, v80
	v_exp_f32_e32 v219, v85
	v_add_f32_e32 v80, v216, v80
	v_exp_f32_e32 v222, v86
	v_add_f32_e32 v80, v217, v80
	v_add_f32_e32 v80, v218, v80
	v_add_f32_e32 v80, v219, v80
	v_exp_f32_e32 v96, v96
	v_exp_f32_e32 v97, v97
	v_exp_f32_e32 v98, v98
	v_exp_f32_e32 v99, v99
	v_exp_f32_e32 v100, v100
	v_exp_f32_e32 v101, v101
	v_exp_f32_e32 v102, v102
	v_exp_f32_e32 v188, v87
	v_exp_f32_e32 v189, v103
	v_exp_f32_e32 v186, v88
	v_exp_f32_e32 v187, v104
	v_exp_f32_e32 v190, v89
	v_exp_f32_e32 v191, v105
	v_exp_f32_e32 v192, v90
	v_exp_f32_e32 v193, v106
	v_exp_f32_e32 v180, v91
	v_exp_f32_e32 v181, v107
	v_exp_f32_e32 v182, v92
	v_exp_f32_e32 v183, v108
	v_exp_f32_e32 v184, v93
	v_exp_f32_e32 v185, v109
	v_exp_f32_e32 v176, v94
	v_exp_f32_e32 v177, v110
	v_exp_f32_e32 v178, v95
	v_exp_f32_e32 v179, v111
	v_add_f32_e32 v194, v222, v80
	v_add_u32_e32 v239, 0x3000, v195
	ds_read2_b64 v[80:83], v239 offset1:2
	v_cvt_pk_bf16_f32 v84, v214, v215
	v_cvt_pk_bf16_f32 v85, v216, v217
	v_cvt_pk_bf16_f32 v86, v218, v219
	v_cvt_pk_bf16_f32 v87, v222, v188
	v_cvt_pk_bf16_f32 v88, v96, v97
	v_cvt_pk_bf16_f32 v89, v98, v99
	v_cvt_pk_bf16_f32 v90, v100, v101
	v_cvt_pk_bf16_f32 v91, v102, v189
	v_add_u32_e32 v240, 0x4000, v195
	s_waitcnt lgkmcnt(0)
	v_mfma_f32_32x32x16_bf16 v[48:63], v[80:83], v[84:87], v[48:63]
	v_mfma_f32_32x32x16_bf16 v[32:47], v[80:83], v[88:91], v[32:47]
	ds_read2_b64 v[80:83], v240 offset0:32 offset1:34
	ds_read2_b64 v[214:217], v239 offset0:4 offset1:6
	ds_read2_b64 v[222:225], v240 offset0:36 offset1:38
	s_waitcnt lgkmcnt(2)
	v_mfma_f32_32x32x16_bf16 v[16:31], v[80:83], v[84:87], v[16:31]
	v_add_f32_e32 v84, 0, v96
	v_add_f32_e32 v84, v97, v84
	v_add_f32_e32 v84, v98, v84
	v_add_f32_e32 v84, v99, v84
	v_add_f32_e32 v84, v100, v84
	v_add_f32_e32 v84, v101, v84
	v_add_f32_e32 v195, v102, v84
	v_mfma_f32_32x32x16_bf16 v[0:15], v[80:83], v[88:91], v[0:15]
	ds_read_b128 v[226:229], v168 offset:6144
	ds_read_b128 v[242:245], v213 offset:32
	ds_read_b128 v[230:233], v168 offset:6208
	ds_read_b128 v[246:249], v213 offset:96
	ds_read_b128 v[234:237], v168 offset:6272
	s_waitcnt lgkmcnt(4)
	v_mfma_f32_32x32x16_bf16 v[80:95], v[226:229], v[152:155], v[64:79]
	v_mfma_f32_32x32x16_bf16 v[96:111], v[226:229], v[156:159], v[64:79]
	ds_read_b128 v[226:229], v213 offset:160
	s_waitcnt lgkmcnt(4)
	v_mfma_f32_32x32x16_bf16 v[80:95], v[242:245], v[136:139], v[80:95]
	v_mfma_f32_32x32x16_bf16 v[96:111], v[242:245], v[140:143], v[96:111]
	s_waitcnt lgkmcnt(3)
	v_mfma_f32_32x32x16_bf16 v[80:95], v[230:233], v[144:147], v[80:95]
	v_mfma_f32_32x32x16_bf16 v[96:111], v[230:233], v[148:151], v[96:111]
	s_waitcnt lgkmcnt(2)
	v_mfma_f32_32x32x16_bf16 v[80:95], v[246:249], v[112:115], v[80:95]
	v_mfma_f32_32x32x16_bf16 v[96:111], v[246:249], v[124:127], v[96:111]
	s_waitcnt lgkmcnt(1)
	v_mfma_f32_32x32x16_bf16 v[80:95], v[234:237], v[128:131], v[80:95]
	v_mfma_f32_32x32x16_bf16 v[96:111], v[234:237], v[132:135], v[96:111]
	s_waitcnt lgkmcnt(0)
; #define MFMA(a, b, c) __builtin_amdgcn_mfma_f32_32x32x16_bf16((a), (b), (c), 0, 0, 0)
; DI unsigned pk_bf16(float lo, float hi) { f32x2v v = {lo, hi}; bf16x2v b = __builtin_convertvector(v, bf16x2v); return __builtin_bit_cast(unsigned, b); }
; #define SB_ __builtin_amdgcn_sched_barrier(0)
; #define ATT64_STORE(base) do { \
;     { uint2* d = (uint2*)((base) + vlo0); d[0] = make_uint2(rv0.x, rv0.y); d[1] = make_uint2(rv0.z, rv0.w); } } while (0)
; DI void attn_item64(const Params& p, int it, char* smem) {
;     ...
;       { const bf16x8 kf = *(const bf16x8*)(kpe); sa = MFMA(kf, qfa[0], sinit); sb = MFMA(kf, qfb[0], sinit); }
; #pragma unroll
;       for (int c = 1; c < 6; ++c) { const bf16x8 kf = *(const bf16x8*)(((c & 1) ? kpo : kpe) + c * 32); sa = MFMA(kf, qfa[c], sa); sb = MFMA(kf, qfb[c], sb); }
;       SB_;
;       float lsa = 0.f, lsb = 0.f;
; #pragma unroll
;       for (int i = 0; i < 16; ++i) { const float e = __builtin_amdgcn_exp2f(sa[i]); sa[i] = e; lsa += e; const float f = __builtin_amdgcn_exp2f(sb[i]); sb[i] = f; lsb += f; }
;       la += lsa; lb += lsb;
;       SB_;
; #pragma unroll
;       for (int s2 = 0; s2 < 2; ++s2) {
;         uint4 pu, pv;
;         pu.x = pk_bf16(sa[8 * s2 + 0], sa[8 * s2 + 1]); pu.y = pk_bf16(sa[8 * s2 + 2], sa[8 * s2 + 3]); pu.z = pk_bf16(sa[8 * s2 + 4], sa[8 * s2 + 5]); pu.w = pk_bf16(sa[8 * s2 + 6], sa[8 * s2 + 7]);
;         pv.x = pk_bf16(sb[8 * s2 + 0], sb[8 * s2 + 1]); pv.y = pk_bf16(sb[8 * s2 + 2], sb[8 * s2 + 3]); pv.z = pk_bf16(sb[8 * s2 + 4], sb[8 * s2 + 5]); pv.w = pk_bf16(sb[8 * s2 + 6], sb[8 * s2 + 7]);
;         const bf16x8 pa_ = __builtin_bit_cast(bf16x8, pu), pb_ = __builtin_bit_cast(bf16x8, pv);
; #pragma unroll
;         for (int vt = 0; vt < 2; ++vt) {
;           const char* vp = cur + KBYTES + (vt * 32 + r) * VROW + (t2 * 32 + 16 * s2 + 4 * hh) * 2;
;           const uint2 lo = *(const uint2*)(vp), hi = *(const uint2*)(vp + 16);
;           uint4 vu; vu.x = lo.x; vu.y = lo.y; vu.z = hi.x; vu.w = hi.y;
;           const bf16x8 vf = __builtin_bit_cast(bf16x8, vu);
;           oa[vt] = MFMA(vf, pa_, oa[vt]);
;           ob[vt] = MFMA(vf, pb_, ob[vt]);
;         }
;       }
;       SB_;
;     }
;     SB_;
;     if (more) { char* nxt = smem + ((kt + 1) & 1) * STAGE; ATT64_STORE(nxt); }
;     __syncthreads();
	v_mfma_f32_32x32x16_bf16 v[80:95], v[226:229], v[116:119], v[80:95]
	v_mfma_f32_32x32x16_bf16 v[96:111], v[226:229], v[120:123], v[96:111]
	s_nop 10
	v_exp_f32_e32 v168, v80
	v_exp_f32_e32 v213, v81
	v_exp_f32_e32 v233, v96
	v_exp_f32_e32 v96, v82
	v_exp_f32_e32 v234, v97
	v_exp_f32_e32 v97, v83
	v_add_f32_e32 v80, 0, v168
	v_exp_f32_e32 v235, v98
	v_exp_f32_e32 v98, v84
	v_add_f32_e32 v80, v213, v80
	v_exp_f32_e32 v236, v99
	v_exp_f32_e32 v99, v85
	v_add_f32_e32 v80, v96, v80
	v_add_f32_e32 v80, v97, v80
	v_add_f32_e32 v80, v98, v80
	v_exp_f32_e32 v237, v100
	v_exp_f32_e32 v241, v101
	v_exp_f32_e32 v100, v86
	v_exp_f32_e32 v101, v102
	v_exp_f32_e32 v102, v87
	v_exp_f32_e32 v103, v103
	v_exp_f32_e32 v218, v88
	v_exp_f32_e32 v219, v104
	v_exp_f32_e32 v104, v89
	v_exp_f32_e32 v105, v105
	v_exp_f32_e32 v226, v90
	v_exp_f32_e32 v227, v106
	v_exp_f32_e32 v106, v91
	v_exp_f32_e32 v107, v107
	v_exp_f32_e32 v228, v92
	v_exp_f32_e32 v229, v108
	v_exp_f32_e32 v108, v93
	v_exp_f32_e32 v109, v109
	v_exp_f32_e32 v230, v94
	v_exp_f32_e32 v231, v110
	v_exp_f32_e32 v110, v95
	v_exp_f32_e32 v111, v111
	v_add_f32_e32 v232, v99, v80
	v_cvt_pk_bf16_f32 v80, v186, v190
	v_cvt_pk_bf16_f32 v81, v192, v180
	v_cvt_pk_bf16_f32 v82, v182, v184
	v_cvt_pk_bf16_f32 v83, v176, v178
	v_cvt_pk_bf16_f32 v84, v187, v191
	v_cvt_pk_bf16_f32 v85, v193, v181
	v_mfma_f32_32x32x16_bf16 v[48:63], v[214:217], v[80:83], v[48:63]
	v_cvt_pk_bf16_f32 v86, v183, v185
	v_cvt_pk_bf16_f32 v87, v177, v179
	v_cvt_pk_bf16_f32 v88, v233, v234
	v_cvt_pk_bf16_f32 v89, v235, v236
	v_cvt_pk_bf16_f32 v90, v237, v241
	v_cvt_pk_bf16_f32 v91, v101, v103
	v_mfma_f32_32x32x16_bf16 v[16:31], v[222:225], v[80:83], v[16:31]
	ds_read2_b64 v[80:83], v239 offset0:8 offset1:10
	v_mfma_f32_32x32x16_bf16 v[32:47], v[214:217], v[84:87], v[32:47]
	v_mfma_f32_32x32x16_bf16 v[0:15], v[222:225], v[84:87], v[0:15]
	v_cvt_pk_bf16_f32 v84, v168, v213
	v_cvt_pk_bf16_f32 v85, v96, v97
	v_cvt_pk_bf16_f32 v86, v98, v99
	v_cvt_pk_bf16_f32 v87, v100, v102
	s_waitcnt lgkmcnt(0)
	s_nop 0
	v_mfma_f32_32x32x16_bf16 v[48:63], v[80:83], v[84:87], v[48:63]
	v_mfma_f32_32x32x16_bf16 v[32:47], v[80:83], v[88:91], v[32:47]
	ds_read2_b64 v[80:83], v240 offset0:40 offset1:42
	ds_read2_b64 v[92:95], v239 offset0:12 offset1:14
	ds_read2_b64 v[96:99], v240 offset0:44 offset1:46
	s_waitcnt lgkmcnt(2)
	v_mfma_f32_32x32x16_bf16 v[16:31], v[80:83], v[84:87], v[16:31]
	v_add_f32_e32 v84, 0, v233
	v_add_f32_e32 v84, v234, v84
	v_add_f32_e32 v84, v235, v84
	v_add_f32_e32 v84, v236, v84
	v_add_f32_e32 v84, v237, v84
	v_add_f32_e32 v233, v241, v84
	v_pk_add_f32 v[84:85], v[188:189], v[194:195]
	v_mfma_f32_32x32x16_bf16 v[0:15], v[80:83], v[88:91], v[0:15]
	v_add_f32_e64 v80, v186, v84
	v_add_f32_e64 v81, v187, v85
	v_add_f32_e64 v90, v100, v232
	v_add_f32_e64 v91, v101, v233
	v_add_f32_e64 v80, v190, v80
	v_add_f32_e64 v81, v191, v81
	v_pk_add_f32 v[90:91], v[102:103], v[90:91]
	v_pk_add_f32 v[84:85], v[192:193], v[80:81]
	v_cvt_pk_bf16_f32 v80, v218, v104
	v_pk_add_f32 v[84:85], v[180:181], v[84:85]
	v_cvt_pk_bf16_f32 v81, v226, v106
	v_pk_add_f32 v[84:85], v[182:183], v[84:85]
	v_cvt_pk_bf16_f32 v82, v228, v108
	v_cvt_pk_bf16_f32 v83, v230, v110
	v_pk_add_f32 v[88:89], v[184:185], v[84:85]
	v_cvt_pk_bf16_f32 v84, v219, v105
	v_cvt_pk_bf16_f32 v85, v227, v107
	v_cvt_pk_bf16_f32 v86, v229, v109
	v_cvt_pk_bf16_f32 v87, v231, v111
	v_pk_add_f32 v[90:91], v[218:219], v[90:91]
	s_waitcnt lgkmcnt(1)
	v_mfma_f32_32x32x16_bf16 v[48:63], v[92:95], v[80:83], v[48:63]
	v_add_f32_e64 v90, v104, v90
	v_add_f32_e64 v91, v105, v91
	v_add_f32_e64 v88, v176, v88
	v_add_f32_e64 v89, v177, v89
	v_add_f32_e64 v88, v178, v88
	v_add_f32_e64 v89, v179, v89
	v_pk_add_f32 v[88:89], v[166:167], v[88:89]
	v_mfma_f32_32x32x16_bf16 v[32:47], v[92:95], v[84:87], v[32:47]
	s_waitcnt lgkmcnt(0)
	v_mfma_f32_32x32x16_bf16 v[16:31], v[96:99], v[80:83], v[16:31]
	v_add_f32_e64 v80, v226, v90
	v_add_f32_e64 v81, v227, v91
	v_add_f32_e64 v80, v106, v80
	v_add_f32_e64 v81, v107, v81
	v_add_f32_e64 v80, v228, v80
	v_add_f32_e64 v81, v229, v81
	v_pk_add_f32 v[80:81], v[108:109], v[80:81]
	v_mfma_f32_32x32x16_bf16 v[0:15], v[96:99], v[84:87], v[0:15]
	v_add_f32_e64 v80, v230, v80
	v_add_f32_e64 v81, v231, v81
	v_add_f32_e64 v80, v110, v80
	v_add_f32_e64 v81, v111, v81
	v_add_f32_e64 v166, v88, v80
	v_add_f32_e64 v167, v89, v81
	s_add_i32 s8, s8, 1
	v_lshl_add_u64 v[170:171], v[170:171], 0, s[30:31]
	v_lshl_add_u64 v[172:173], v[172:173], 0, s[34:35]
	s_cmp_lg_u32 s8, 36
	v_lshl_add_u64 v[174:175], v[174:175], 0, s[34:35]
	s_waitcnt vmcnt(0)
	ds_write2_b64 v238, v[160:161], v[162:163] offset1:1
	s_waitcnt lgkmcnt(0)
	s_barrier
	s_cbranch_scc0 .LBB0_551
